# attention steady loop: no exps behind the last P.V MFMA of a step; the closing wait and barrier follow it directly
# speedup vs baseline: 1.0051x; 1.0021x over previous
.LBB0_311:
	v_exp_f32_e32 v128, v128
	v_exp_f32_e32 v129, v129
	v_exp_f32_e32 v130, v130
	ds_read_b64_tr_b16 v[108:109], v217 offset:34816
	ds_read_b64_tr_b16 v[110:111], v217 offset:35328
	v_mfma_f32_32x32x16_bf16 v[48:63], v[148:151], v[80:83], v[48:63]
	v_exp_f32_e32 v131, v131
	v_exp_f32_e32 v132, v132
	v_exp_f32_e32 v133, v133
	ds_read_b64_tr_b16 v[188:189], v217 offset:38912
	ds_read_b64_tr_b16 v[190:191], v217 offset:39424
	s_waitcnt lgkmcnt(12)
	v_mfma_f32_32x32x16_bf16 v[32:47], v[144:147], v[84:87], v[32:47]
	v_exp_f32_e32 v134, v134
	v_exp_f32_e32 v135, v135
	v_exp_f32_e32 v136, v136
	ds_read_b64_tr_b16 v[84:85], v217 offset:35840
	ds_read_b64_tr_b16 v[86:87], v217 offset:36352
	v_mfma_f32_32x32x16_bf16 v[48:63], v[144:147], v[88:91], v[48:63]
	v_exp_f32_e32 v137, v137
	v_exp_f32_e32 v138, v138
	v_exp_f32_e32 v139, v139
	ds_read_b64_tr_b16 v[88:89], v217 offset:39936
	ds_read_b64_tr_b16 v[90:91], v217 offset:40448
	s_waitcnt lgkmcnt(12)
	v_mfma_f32_32x32x16_bf16 v[16:31], v[164:167], v[92:95], v[16:31]
	v_exp_f32_e32 v140, v140
	v_exp_f32_e32 v141, v141
	v_exp_f32_e32 v142, v142
	v_add_u32_e32 v92, s22, v247
	ds_read_b128 v[80:83], v92
	ds_read_b128 v[200:203], v92 offset:512
	v_mfma_f32_32x32x16_bf16 v[0:15], v[164:167], v[96:99], v[0:15]
	v_exp_f32_e32 v143, v143
	v_exp_f32_e32 v112, v112
	v_exp_f32_e32 v113, v113
	ds_read_b128 v[204:207], v92 offset:2048
	ds_read_b128 v[196:199], v92 offset:2560
	s_waitcnt lgkmcnt(12)
	v_mfma_f32_32x32x16_bf16 v[16:31], v[156:159], v[100:103], v[16:31]
	v_exp_f32_e32 v114, v114
	v_exp_f32_e32 v115, v115
	v_exp_f32_e32 v116, v116
	ds_read_b128 v[192:195], v92 offset:4096
	ds_read_b128 v[184:187], v92 offset:4608
	v_mfma_f32_32x32x16_bf16 v[0:15], v[156:159], v[104:107], v[0:15]
	v_exp_f32_e32 v117, v117
	v_exp_f32_e32 v118, v118
	v_exp_f32_e32 v119, v119
	ds_read_b128 v[180:183], v92 offset:6144
	ds_read_b128 v[176:179], v92 offset:6656
	s_waitcnt lgkmcnt(12)
	v_mfma_f32_32x32x16_bf16 v[16:31], v[148:151], v[108:111], v[16:31]
	v_exp_f32_e32 v120, v120
	v_exp_f32_e32 v121, v121
	v_exp_f32_e32 v122, v122
	v_mfma_f32_32x32x16_bf16 v[0:15], v[148:151], v[188:191], v[0:15]
	v_exp_f32_e32 v123, v123
	v_exp_f32_e32 v124, v124
	v_exp_f32_e32 v125, v125
	s_waitcnt lgkmcnt(8)
	v_mfma_f32_32x32x16_bf16 v[16:31], v[144:147], v[84:87], v[16:31]
	v_exp_f32_e32 v126, v126
	v_exp_f32_e32 v127, v127
	v_mfma_f32_32x32x16_bf16 v[0:15], v[144:147], v[88:91], v[0:15]
	s_waitcnt vmcnt(3) lgkmcnt(0)
	s_barrier
	s_cmp_eq_u64 s[20:21], 0
	s_cbranch_scc1 .LBB0_313
	s_waitcnt lgkmcnt(0)
	v_add_u32_e32 v208, s65, v248
	ds_read_b128 v[84:87], v208 offset:96
	ds_read_b128 v[88:91], v208 offset:64
	ds_read_b128 v[92:95], v208 offset:32
	ds_read_b128 v[96:99], v208
	s_waitcnt lgkmcnt(3)
	v_pk_mul_f32 v[44:45], v[44:45], v[84:85]
	s_waitcnt lgkmcnt(2)
	v_pk_mul_f32 v[40:41], v[40:41], v[88:89]
	s_waitcnt lgkmcnt(1)
	v_pk_mul_f32 v[36:37], v[36:37], v[92:93]
	v_pk_mul_f32 v[46:47], v[46:47], v[86:87]
	v_pk_mul_f32 v[42:43], v[42:43], v[90:91]
	v_pk_mul_f32 v[38:39], v[38:39], v[94:95]
	s_waitcnt lgkmcnt(0)
	v_pk_mul_f32 v[34:35], v[34:35], v[98:99]
	v_pk_mul_f32 v[32:33], v[32:33], v[96:97]
	v_pk_mul_f32 v[60:61], v[60:61], v[84:85]
	v_pk_mul_f32 v[56:57], v[56:57], v[88:89]
	v_pk_mul_f32 v[52:53], v[52:53], v[92:93]
	v_pk_mul_f32 v[62:63], v[62:63], v[86:87]
	v_pk_mul_f32 v[58:59], v[58:59], v[90:91]
	v_pk_mul_f32 v[54:55], v[54:55], v[94:95]
	v_pk_mul_f32 v[50:51], v[50:51], v[98:99]
	v_pk_mul_f32 v[48:49], v[48:49], v[96:97]
	v_pk_mul_f32 v[28:29], v[28:29], v[84:85]
	v_pk_mul_f32 v[24:25], v[24:25], v[88:89]
	v_pk_mul_f32 v[20:21], v[20:21], v[92:93]
	v_pk_mul_f32 v[30:31], v[30:31], v[86:87]
	v_pk_mul_f32 v[26:27], v[26:27], v[90:91]
	v_pk_mul_f32 v[22:23], v[22:23], v[94:95]
	v_pk_mul_f32 v[18:19], v[18:19], v[98:99]
	v_pk_mul_f32 v[16:17], v[16:17], v[96:97]
	v_pk_mul_f32 v[12:13], v[12:13], v[84:85]
	v_pk_mul_f32 v[8:9], v[8:9], v[88:89]
	v_pk_mul_f32 v[4:5], v[4:5], v[92:93]
	v_pk_mul_f32 v[14:15], v[14:15], v[86:87]
	v_pk_mul_f32 v[10:11], v[10:11], v[90:91]
	v_pk_mul_f32 v[6:7], v[6:7], v[94:95]
	v_pk_mul_f32 v[2:3], v[2:3], v[98:99]
	v_pk_mul_f32 v[0:1], v[0:1], v[96:97]

.LBB0_314:
	v_exp_f32_e32 v96, v96
	v_exp_f32_e32 v97, v97
	v_exp_f32_e32 v98, v98
	ds_read_b64_tr_b16 v[140:141], v209 offset:34816
	ds_read_b64_tr_b16 v[142:143], v209 offset:35328
	v_mfma_f32_32x32x16_bf16 v[48:63], v[148:151], v[112:115], v[48:63]
	v_exp_f32_e32 v99, v99
	v_exp_f32_e32 v100, v100
	v_exp_f32_e32 v101, v101
	ds_read_b64_tr_b16 v[112:113], v209 offset:38912
	ds_read_b64_tr_b16 v[114:115], v209 offset:39424
	s_waitcnt lgkmcnt(12)
	v_mfma_f32_32x32x16_bf16 v[32:47], v[144:147], v[116:119], v[32:47]
	v_exp_f32_e32 v102, v102
	v_exp_f32_e32 v103, v103
	v_exp_f32_e32 v104, v104
	ds_read_b64_tr_b16 v[116:117], v209 offset:35840
	ds_read_b64_tr_b16 v[118:119], v209 offset:36352
	v_mfma_f32_32x32x16_bf16 v[48:63], v[144:147], v[120:123], v[48:63]
	v_exp_f32_e32 v105, v105
	v_exp_f32_e32 v106, v106
	v_exp_f32_e32 v107, v107
	ds_read_b64_tr_b16 v[120:121], v209 offset:39936
	ds_read_b64_tr_b16 v[122:123], v209 offset:40448
	s_waitcnt lgkmcnt(12)
	v_mfma_f32_32x32x16_bf16 v[16:31], v[164:167], v[124:127], v[16:31]
	v_exp_f32_e32 v108, v108
	v_exp_f32_e32 v109, v109
	v_exp_f32_e32 v110, v110
	v_add_u32_e32 v124, s66, v247
	ds_read_b128 v[204:207], v124
	ds_read_b128 v[200:203], v124 offset:512
	v_mfma_f32_32x32x16_bf16 v[0:15], v[164:167], v[128:131], v[0:15]
	v_exp_f32_e32 v111, v111
	v_exp_f32_e32 v80, v80
	v_exp_f32_e32 v81, v81
	ds_read_b128 v[196:199], v124 offset:2048
	ds_read_b128 v[192:195], v124 offset:2560
	s_waitcnt lgkmcnt(12)
	v_mfma_f32_32x32x16_bf16 v[16:31], v[156:159], v[132:135], v[16:31]
	v_exp_f32_e32 v82, v82
	v_exp_f32_e32 v83, v83
	v_exp_f32_e32 v84, v84
	ds_read_b128 v[188:191], v124 offset:4096
	ds_read_b128 v[184:187], v124 offset:4608
	v_mfma_f32_32x32x16_bf16 v[0:15], v[156:159], v[136:139], v[0:15]
	v_exp_f32_e32 v85, v85
	v_exp_f32_e32 v86, v86
	v_exp_f32_e32 v87, v87
	ds_read_b128 v[180:183], v124 offset:6144
	ds_read_b128 v[176:179], v124 offset:6656
	s_waitcnt lgkmcnt(12)
	v_mfma_f32_32x32x16_bf16 v[16:31], v[148:151], v[140:143], v[16:31]
	v_exp_f32_e32 v88, v88
	v_exp_f32_e32 v89, v89
	v_exp_f32_e32 v90, v90
	v_mfma_f32_32x32x16_bf16 v[0:15], v[148:151], v[112:115], v[0:15]
	v_exp_f32_e32 v91, v91
	v_exp_f32_e32 v92, v92
	v_exp_f32_e32 v93, v93
	s_waitcnt lgkmcnt(8)
	v_mfma_f32_32x32x16_bf16 v[16:31], v[144:147], v[116:119], v[16:31]
	v_exp_f32_e32 v94, v94
	v_exp_f32_e32 v95, v95
	v_mfma_f32_32x32x16_bf16 v[0:15], v[144:147], v[120:123], v[0:15]
	s_waitcnt vmcnt(3) lgkmcnt(0)
	s_barrier
	s_cmp_eq_u64 s[20:21], 0
	s_cbranch_scc1 .LBB0_316
	s_waitcnt lgkmcnt(0)
	v_add_u32_e32 v208, s65, v248
	ds_read_b128 v[112:115], v208 offset:96
	ds_read_b128 v[116:119], v208 offset:64
	ds_read_b128 v[120:123], v208 offset:32
	ds_read_b128 v[124:127], v208
	s_waitcnt lgkmcnt(3)
	v_pk_mul_f32 v[44:45], v[44:45], v[112:113]
	s_waitcnt lgkmcnt(2)
	v_pk_mul_f32 v[40:41], v[40:41], v[116:117]
	s_waitcnt lgkmcnt(1)
	v_pk_mul_f32 v[36:37], v[36:37], v[120:121]
	v_pk_mul_f32 v[46:47], v[46:47], v[114:115]
	v_pk_mul_f32 v[42:43], v[42:43], v[118:119]
	v_pk_mul_f32 v[38:39], v[38:39], v[122:123]
	s_waitcnt lgkmcnt(0)
	v_pk_mul_f32 v[34:35], v[34:35], v[126:127]
	v_pk_mul_f32 v[32:33], v[32:33], v[124:125]
	v_pk_mul_f32 v[60:61], v[60:61], v[112:113]
	v_pk_mul_f32 v[56:57], v[56:57], v[116:117]
	v_pk_mul_f32 v[52:53], v[52:53], v[120:121]
	v_pk_mul_f32 v[62:63], v[62:63], v[114:115]
	v_pk_mul_f32 v[58:59], v[58:59], v[118:119]
	v_pk_mul_f32 v[54:55], v[54:55], v[122:123]
	v_pk_mul_f32 v[50:51], v[50:51], v[126:127]
	v_pk_mul_f32 v[48:49], v[48:49], v[124:125]
	v_pk_mul_f32 v[28:29], v[28:29], v[112:113]
	v_pk_mul_f32 v[24:25], v[24:25], v[116:117]
	v_pk_mul_f32 v[20:21], v[20:21], v[120:121]
	v_pk_mul_f32 v[30:31], v[30:31], v[114:115]
	v_pk_mul_f32 v[26:27], v[26:27], v[118:119]
	v_pk_mul_f32 v[22:23], v[22:23], v[122:123]
	v_pk_mul_f32 v[18:19], v[18:19], v[126:127]
	v_pk_mul_f32 v[16:17], v[16:17], v[124:125]
	v_pk_mul_f32 v[12:13], v[12:13], v[112:113]
	v_pk_mul_f32 v[8:9], v[8:9], v[116:117]
	v_pk_mul_f32 v[4:5], v[4:5], v[120:121]
	v_pk_mul_f32 v[14:15], v[14:15], v[114:115]
	v_pk_mul_f32 v[10:11], v[10:11], v[118:119]
	v_pk_mul_f32 v[6:7], v[6:7], v[122:123]
	v_pk_mul_f32 v[2:3], v[2:3], v[126:127]
	v_pk_mul_f32 v[0:1], v[0:1], v[124:125]
